# phase F first epilogue: all 16 per-quad gate loads issued at the start of the epilogue, counted vmcnt waits (was one load per vmcnt(0))
# baseline (speedup 1.0000x reference)
; DI uint2 pk4(float a, float b, float c, float d) { uint2 o; o.x = pk2(a, b); o.y = pk2(c, d); return o; }
; DI float sigmoidf_(float x) { return 1.f / (1.f + __expf(-x)); }
; DI void phaseF(int wv0, PP p, unsigned char* smem) {
;     ...
;             for (int j = 0; j < 4; ++j) acc[ai][0][m][n][j] *= sigmoidf_(acc[ai][1][m][n][j]);
;       __builtin_amdgcn_sched_barrier(0);
;       epi256(wv0, acc, brow, grp * 128, [&](int ai, int bj, int m, int n, int row, int col0, f32x4& v) {
;         if (bj == 0) {
;           const unsigned og = (unsigned)row * 2048u + 1024u + (unsigned)col0, om = (unsigned)row * 1024u + (unsigned)col0;
;           const uint2 gq = *(const uint2*)(MG + og);
;           *(uint2*)(MR + om) = pk4(__uint_as_float(gq.x << 16) * v[0], __uint_as_float(gq.x & 0xffff0000u) * v[1],
;                                    __uint_as_float(gq.y << 16) * v[2], __uint_as_float(gq.y & 0xffff0000u) * v[3]);
.LBB0_982:
	v_mul_f32_e32 v116, 0xbfb8aa3b, v116
	v_exp_f32_e32 v140, v116
	v_mul_f32_e32 v116, 0xbfb8aa3b, v117
	v_mul_f32_e32 v76, 0xbfb8aa3b, v76
	v_exp_f32_e32 v141, v116
	v_mul_f32_e32 v116, 0xbfb8aa3b, v118
	v_exp_f32_e32 v118, v76
	v_mul_f32_e32 v76, 0xbfb8aa3b, v77
	v_exp_f32_e32 v138, v116
	v_mul_f32_e32 v116, 0xbfb8aa3b, v119
	v_exp_f32_e32 v119, v76
	v_mul_f32_e32 v76, 0xbfb8aa3b, v78
	v_exp_f32_e32 v139, v116
	v_mul_f32_e32 v108, 0xbfb8aa3b, v108
	v_exp_f32_e32 v116, v76
	v_mul_f32_e32 v76, 0xbfb8aa3b, v79
	v_exp_f32_e32 v136, v108
	v_mul_f32_e32 v108, 0xbfb8aa3b, v109
	v_exp_f32_e32 v117, v76
	v_mul_f32_e32 v76, 0xbfb8aa3b, v112
	v_exp_f32_e32 v137, v108
	v_mul_f32_e32 v108, 0xbfb8aa3b, v110
	v_exp_f32_e32 v110, v76
	v_mul_f32_e32 v76, 0xbfb8aa3b, v113
	v_exp_f32_e32 v134, v108
	v_mul_f32_e32 v108, 0xbfb8aa3b, v111
	v_exp_f32_e32 v111, v76
	v_mul_f32_e32 v76, 0xbfb8aa3b, v114
	v_exp_f32_e32 v135, v108
	v_mul_f32_e32 v100, 0xbfb8aa3b, v100
	v_exp_f32_e32 v108, v76
	v_mul_f32_e32 v76, 0xbfb8aa3b, v115
	v_exp_f32_e32 v132, v100
	v_mul_f32_e32 v100, 0xbfb8aa3b, v101
	v_exp_f32_e32 v109, v76
	v_mul_f32_e32 v76, 0xbfb8aa3b, v104
	v_exp_f32_e32 v133, v100
	v_mul_f32_e32 v100, 0xbfb8aa3b, v102
	v_exp_f32_e32 v102, v76
	v_mul_f32_e32 v76, 0xbfb8aa3b, v105
	v_mul_f32_e32 v124, 0xbfb8aa3b, v124
	v_exp_f32_e32 v130, v100
	v_mul_f32_e32 v100, 0xbfb8aa3b, v103
	v_exp_f32_e32 v103, v76
	v_mul_f32_e32 v76, 0xbfb8aa3b, v106
	v_exp_f32_e32 v152, v124
	v_mul_f32_e32 v124, 0xbfb8aa3b, v125
	v_exp_f32_e32 v131, v100
	v_mul_f32_e32 v92, 0xbfb8aa3b, v92
	v_exp_f32_e32 v100, v76
	v_mul_f32_e32 v76, 0xbfb8aa3b, v107
	v_exp_f32_e32 v153, v124
	v_mul_f32_e32 v124, 0xbfb8aa3b, v126
	v_exp_f32_e32 v126, v92
	v_mul_f32_e32 v92, 0xbfb8aa3b, v93
	v_exp_f32_e32 v101, v76
	v_mul_f32_e32 v76, 0xbfb8aa3b, v96
	v_exp_f32_e32 v146, v124
	v_mul_f32_e32 v124, 0xbfb8aa3b, v127
	v_exp_f32_e32 v127, v92
	v_mul_f32_e32 v92, 0xbfb8aa3b, v94
	v_exp_f32_e32 v94, v76
	v_mul_f32_e32 v76, 0xbfb8aa3b, v97
	v_exp_f32_e32 v147, v124
	v_mul_f32_e32 v120, 0xbfb8aa3b, v120
	v_exp_f32_e32 v124, v92
	v_mul_f32_e32 v92, 0xbfb8aa3b, v95
	v_exp_f32_e32 v95, v76
	v_mul_f32_e32 v76, 0xbfb8aa3b, v98
	v_exp_f32_e32 v144, v120
	v_mul_f32_e32 v120, 0xbfb8aa3b, v121
	v_exp_f32_e32 v125, v92
	v_mul_f32_e32 v84, 0xbfb8aa3b, v84
	v_exp_f32_e32 v92, v76
	v_mul_f32_e32 v76, 0xbfb8aa3b, v99
	v_exp_f32_e32 v145, v120
	v_mul_f32_e32 v120, 0xbfb8aa3b, v122
	v_exp_f32_e32 v122, v84
	v_mul_f32_e32 v84, 0xbfb8aa3b, v85
	v_exp_f32_e32 v93, v76
	v_mul_f32_e32 v76, 0xbfb8aa3b, v88
	v_exp_f32_e32 v142, v120
	v_mul_f32_e32 v120, 0xbfb8aa3b, v123
	v_exp_f32_e32 v123, v84
	v_mul_f32_e32 v84, 0xbfb8aa3b, v86
	v_exp_f32_e32 v86, v76
	v_mul_f32_e32 v76, 0xbfb8aa3b, v89
	v_exp_f32_e32 v143, v120
	v_exp_f32_e32 v120, v84
	v_mul_f32_e32 v84, 0xbfb8aa3b, v87
	v_exp_f32_e32 v87, v76
	v_mul_f32_e32 v76, 0xbfb8aa3b, v90
	v_exp_f32_e32 v121, v84
	v_exp_f32_e32 v84, v76
	v_mul_f32_e32 v76, 0xbfb8aa3b, v91
	v_exp_f32_e32 v85, v76
	v_mul_f32_e32 v76, 0xbfb8aa3b, v80
	v_exp_f32_e32 v80, v76
	v_mul_f32_e32 v76, 0xbfb8aa3b, v81
	v_exp_f32_e32 v81, v76
	v_mul_f32_e32 v76, 0xbfb8aa3b, v82
	v_exp_f32_e32 v78, v76
	v_mul_f32_e32 v76, 0xbfb8aa3b, v83
	v_mul_f32_e32 v72, 0xbfb8aa3b, v72
	v_exp_f32_e32 v79, v76
	v_exp_f32_e32 v76, v72
	v_mul_f32_e32 v72, 0xbfb8aa3b, v73
	v_exp_f32_e32 v77, v72
	v_mul_f32_e32 v72, 0xbfb8aa3b, v74
	v_exp_f32_e32 v74, v72
	v_mul_f32_e32 v72, 0xbfb8aa3b, v75
	v_mul_f32_e32 v68, 0xbfb8aa3b, v68
	v_exp_f32_e32 v75, v72
	v_exp_f32_e32 v72, v68
	v_mul_f32_e32 v68, 0xbfb8aa3b, v69
	v_exp_f32_e32 v73, v68
	v_mul_f32_e32 v68, 0xbfb8aa3b, v70
	v_exp_f32_e32 v70, v68
	v_mul_f32_e32 v68, 0xbfb8aa3b, v71
	v_mul_f32_e32 v64, 0xbfb8aa3b, v64
	v_exp_f32_e32 v71, v68
	v_exp_f32_e32 v68, v64
	v_mul_f32_e32 v64, 0xbfb8aa3b, v65
	v_exp_f32_e32 v69, v64
	v_mul_f32_e32 v64, 0xbfb8aa3b, v66
	v_mul_f32_e32 v65, 0xbfb8aa3b, v67
	v_exp_f32_e32 v64, v64
	v_exp_f32_e32 v65, v65
	v_mov_b32_e32 v66, v148
	s_lshl_b32 s10, s33, 7
	v_pk_add_f32 v[96:97], v[152:153], 1.0 op_sel_hi:[1,0]
	v_lshrrev_b32_e32 v67, 2, v66
	v_and_or_b32 v67, v67, 12, s10
	v_and_or_b32 v83, v66, 15, s95
	v_or_b32_e32 v82, s81, v67
	v_lshl_or_b32 v98, v83, 11, v151
	v_or_b32_e32 v128, v98, v82
	v_lshl_add_u64 v[88:89], v[128:129], 1, s[12:13]
	global_load_dwordx2 v[208:209], v[88:89], off
	v_add_co_u32_e32 v200, vcc, 0x20, v88
	v_addc_co_u32_e32 v201, vcc, 0, v89, vcc
	global_load_dwordx2 v[210:211], v[200:201], off
	v_add_co_u32_e32 v200, vcc, 0x10000, v88
	v_addc_co_u32_e32 v201, vcc, 0, v89, vcc
	global_load_dwordx2 v[212:213], v[200:201], off
	v_add_co_u32_e32 v200, vcc, 0x10020, v88
	v_addc_co_u32_e32 v201, vcc, 0, v89, vcc
	global_load_dwordx2 v[214:215], v[200:201], off
	v_add_co_u32_e32 v200, vcc, 0x20000, v88
	v_addc_co_u32_e32 v201, vcc, 0, v89, vcc
	global_load_dwordx2 v[216:217], v[200:201], off
	v_add_co_u32_e32 v200, vcc, 0x20020, v88
	v_addc_co_u32_e32 v201, vcc, 0, v89, vcc
	global_load_dwordx2 v[218:219], v[200:201], off
	v_add_co_u32_e32 v200, vcc, 0x30000, v88
	v_addc_co_u32_e32 v201, vcc, 0, v89, vcc
	global_load_dwordx2 v[220:221], v[200:201], off
	v_add_co_u32_e32 v200, vcc, 0x30020, v88
	v_addc_co_u32_e32 v201, vcc, 0, v89, vcc
	global_load_dwordx2 v[222:223], v[200:201], off
	v_add_co_u32_e32 v200, vcc, 0x80000, v88
	v_addc_co_u32_e32 v201, vcc, 0, v89, vcc
	global_load_dwordx2 v[224:225], v[200:201], off
	v_add_co_u32_e32 v200, vcc, 0x80020, v88
	v_addc_co_u32_e32 v201, vcc, 0, v89, vcc
	global_load_dwordx2 v[226:227], v[200:201], off
	v_add_co_u32_e32 v200, vcc, 0x90000, v88
	v_addc_co_u32_e32 v201, vcc, 0, v89, vcc
	global_load_dwordx2 v[228:229], v[200:201], off
	v_add_co_u32_e32 v200, vcc, 0x90020, v88
	v_addc_co_u32_e32 v201, vcc, 0, v89, vcc
	global_load_dwordx2 v[230:231], v[200:201], off
	v_add_co_u32_e32 v200, vcc, 0xa0000, v88
	v_addc_co_u32_e32 v201, vcc, 0, v89, vcc
	global_load_dwordx2 v[232:233], v[200:201], off
	v_add_co_u32_e32 v200, vcc, 0xa0020, v88
	v_addc_co_u32_e32 v201, vcc, 0, v89, vcc
	global_load_dwordx2 v[234:235], v[200:201], off
	v_add_co_u32_e32 v200, vcc, 0xb0000, v88
	v_addc_co_u32_e32 v201, vcc, 0, v89, vcc
	global_load_dwordx2 v[236:237], v[200:201], off
	v_add_co_u32_e32 v200, vcc, 0xb0020, v88
	v_addc_co_u32_e32 v201, vcc, 0, v89, vcc
	global_load_dwordx2 v[238:239], v[200:201], off
	v_div_scale_f32 v67, s[72:73], v97, v97, 1.0
	v_lshlrev_b32_e32 v99, 10, v83
	v_or_b32_e32 v66, v82, v99
	s_mov_b32 s10, 1
	s_waitcnt vmcnt(15)
; DI uint2 pk4(float a, float b, float c, float d) { uint2 o; o.x = pk2(a, b); o.y = pk2(c, d); return o; }
; DI float sigmoidf_(float x) { return 1.f / (1.f + __expf(-x)); }
; DI void phaseF(int wv0, PP p, unsigned char* smem) {
;     ...
;             for (int j = 0; j < 4; ++j) acc[ai][0][m][n][j] *= sigmoidf_(acc[ai][1][m][n][j]);
;       __builtin_amdgcn_sched_barrier(0);
;       epi256(wv0, acc, brow, grp * 128, [&](int ai, int bj, int m, int n, int row, int col0, f32x4& v) {
;         if (bj == 0) {
;           const unsigned og = (unsigned)row * 2048u + 1024u + (unsigned)col0, om = (unsigned)row * 1024u + (unsigned)col0;
;           const uint2 gq = *(const uint2*)(MG + og);
;           *(uint2*)(MR + om) = pk4(__uint_as_float(gq.x << 16) * v[0], __uint_as_float(gq.x & 0xffff0000u) * v[1],
;                                    __uint_as_float(gq.y << 16) * v[2], __uint_as_float(gq.y & 0xffff0000u) * v[3]);
;         }
	v_mov_b32_e32 v88, v208
	v_mov_b32_e32 v89, v209
	v_lshlrev_b32_e32 v90, 16, v88
	v_and_b32_e32 v91, 0xffff0000, v88
	v_rcp_f32_e32 v88, v67
	s_nop 0
	v_fma_f32 v104, -v67, v88, 1.0
	v_fmac_f32_e32 v88, v104, v88
	v_div_scale_f32 v104, vcc, 1.0, v97, 1.0
	v_mul_f32_e32 v105, v104, v88
	v_fma_f32 v106, -v67, v105, v104
	v_fmac_f32_e32 v105, v106, v88
	v_fma_f32 v67, -v67, v105, v104
	v_div_fmas_f32 v67, v67, v88, v105
	v_div_fixup_f32 v97, v67, v97, 1.0
	v_div_scale_f32 v67, s[72:73], v96, v96, 1.0
	v_rcp_f32_e32 v88, v67
	s_nop 0
	v_fma_f32 v104, -v67, v88, 1.0
	v_fmac_f32_e32 v88, v104, v88
	v_div_scale_f32 v104, vcc, 1.0, v96, 1.0
	v_mul_f32_e32 v105, v104, v88
	v_fma_f32 v106, -v67, v105, v104
	v_fmac_f32_e32 v105, v106, v88
	v_fma_f32 v67, -v67, v105, v104
	v_div_fmas_f32 v67, v67, v88, v105
	v_div_fixup_f32 v96, v67, v96, 1.0
	v_pk_mul_f32 v[60:61], v[60:61], v[96:97]
	v_lshlrev_b32_e32 v88, 16, v89
	v_pk_mul_f32 v[60:61], v[60:61], v[90:91]
	v_pk_add_f32 v[90:91], v[146:147], 1.0 op_sel_hi:[1,0]
	v_and_b32_e32 v89, 0xffff0000, v89
	v_div_scale_f32 v67, s[72:73], v91, v91, 1.0
	v_rcp_f32_e32 v96, v67
	v_cvt_pk_bf16_f32 v60, v60, v61
	v_fma_f32 v97, -v67, v96, 1.0
	v_fmac_f32_e32 v96, v97, v96
	v_div_scale_f32 v97, vcc, 1.0, v91, 1.0
	v_mul_f32_e32 v104, v97, v96
	v_fma_f32 v105, -v67, v104, v97
	v_fmac_f32_e32 v104, v105, v96
	v_fma_f32 v67, -v67, v104, v97
	v_div_fmas_f32 v67, v67, v96, v104
	v_div_fixup_f32 v91, v67, v91, 1.0
	v_div_scale_f32 v67, s[72:73], v90, v90, 1.0
	v_rcp_f32_e32 v96, v67
	s_nop 0
	v_fma_f32 v97, -v67, v96, 1.0
	v_fmac_f32_e32 v96, v97, v96
	v_div_scale_f32 v97, vcc, 1.0, v90, 1.0
	v_mul_f32_e32 v104, v97, v96
	v_fma_f32 v105, -v67, v104, v97
	v_fmac_f32_e32 v104, v105, v96
	v_fma_f32 v67, -v67, v104, v97
	v_div_fmas_f32 v67, v67, v96, v104
	v_div_fixup_f32 v90, v67, v90, 1.0
	v_pk_mul_f32 v[62:63], v[62:63], v[90:91]
	v_mov_b32_e32 v67, v129
	v_pk_mul_f32 v[62:63], v[62:63], v[88:89]
	v_pk_add_f32 v[90:91], v[144:145], 1.0 op_sel_hi:[1,0]
	v_cvt_pk_bf16_f32 v61, v62, v63
	v_lshl_add_u64 v[62:63], v[66:67], 1, s[14:15]
	global_store_dwordx2 v[62:63], v[60:61], off
	v_or_b32_e32 v62, 16, v82
	v_add_u32_e32 v128, v62, v98
	v_lshl_add_u64 v[66:67], v[128:129], 1, s[12:13]
	v_div_scale_f32 v61, s[72:73], v91, v91, 1.0
	v_rcp_f32_e32 v63, v61
	v_add_u32_e32 v60, v62, v99
	s_waitcnt vmcnt(15)
	v_mov_b32_e32 v66, v210
	v_mov_b32_e32 v67, v211
	v_lshlrev_b32_e32 v88, 16, v66
	v_and_b32_e32 v89, 0xffff0000, v66
	v_fma_f32 v66, -v61, v63, 1.0
	v_fmac_f32_e32 v63, v66, v63
	v_div_scale_f32 v66, vcc, 1.0, v91, 1.0
	v_mul_f32_e32 v96, v66, v63
	v_fma_f32 v97, -v61, v96, v66
	v_fmac_f32_e32 v96, v97, v63
	v_fma_f32 v61, -v61, v96, v66
	v_div_fmas_f32 v61, v61, v63, v96
	v_div_fixup_f32 v91, v61, v91, 1.0
	v_div_scale_f32 v61, s[72:73], v90, v90, 1.0
	v_rcp_f32_e32 v63, v61
	s_nop 0
	v_fma_f32 v66, -v61, v63, 1.0
	v_fmac_f32_e32 v63, v66, v63
	v_div_scale_f32 v66, vcc, 1.0, v90, 1.0
	v_mul_f32_e32 v96, v66, v63
	v_fma_f32 v97, -v61, v96, v66
	v_fmac_f32_e32 v96, v97, v63
	v_fma_f32 v61, -v61, v96, v66
	v_div_fmas_f32 v61, v61, v63, v96
	v_div_fixup_f32 v90, v61, v90, 1.0
	v_pk_mul_f32 v[56:57], v[56:57], v[90:91]
	v_lshlrev_b32_e32 v66, 16, v67
	v_pk_mul_f32 v[56:57], v[56:57], v[88:89]
	v_pk_add_f32 v[88:89], v[142:143], 1.0 op_sel_hi:[1,0]
	v_and_b32_e32 v67, 0xffff0000, v67
	v_div_scale_f32 v61, s[72:73], v89, v89, 1.0
	v_rcp_f32_e32 v63, v61
	v_cvt_pk_bf16_f32 v56, v56, v57
	v_fma_f32 v90, -v61, v63, 1.0
	v_fmac_f32_e32 v63, v90, v63
	v_div_scale_f32 v90, vcc, 1.0, v89, 1.0
	v_mul_f32_e32 v91, v90, v63
	v_fma_f32 v96, -v61, v91, v90
	v_fmac_f32_e32 v91, v96, v63
	v_fma_f32 v61, -v61, v91, v90
	v_div_fmas_f32 v61, v61, v63, v91
	v_div_fixup_f32 v89, v61, v89, 1.0
	v_div_scale_f32 v61, s[72:73], v88, v88, 1.0
	v_rcp_f32_e32 v63, v61
	s_nop 0
	v_fma_f32 v90, -v61, v63, 1.0
	v_fmac_f32_e32 v63, v90, v63
	v_div_scale_f32 v90, vcc, 1.0, v88, 1.0
	v_mul_f32_e32 v91, v90, v63
	v_fma_f32 v96, -v61, v91, v90
	v_fmac_f32_e32 v91, v96, v63
	v_fma_f32 v61, -v61, v91, v90
	v_div_fmas_f32 v61, v61, v63, v91
	v_div_fixup_f32 v88, v61, v88, 1.0
	v_pk_mul_f32 v[58:59], v[58:59], v[88:89]
	v_mov_b32_e32 v61, v129
	v_pk_mul_f32 v[58:59], v[58:59], v[66:67]
	v_pk_add_f32 v[66:67], v[140:141], 1.0 op_sel_hi:[1,0]
	v_cvt_pk_bf16_f32 v57, v58, v59
	v_lshl_add_u64 v[58:59], v[60:61], 1, s[14:15]
	global_store_dwordx2 v[58:59], v[56:57], off
	v_or_b32_e32 v56, 16, v83
	v_lshl_or_b32 v63, v56, 11, v151
	v_or_b32_e32 v128, v63, v82
	v_lshl_add_u64 v[58:59], v[128:129], 1, s[12:13]
	v_div_scale_f32 v57, s[72:73], v67, v67, 1.0
	v_lshlrev_b32_e32 v88, 10, v56
	v_or_b32_e32 v56, v88, v82
	v_add_u32_e32 v128, v63, v62
	s_waitcnt vmcnt(15)
; DI uint2 pk4(float a, float b, float c, float d) { uint2 o; o.x = pk2(a, b); o.y = pk2(c, d); return o; }
; DI float sigmoidf_(float x) { return 1.f / (1.f + __expf(-x)); }
; DI void phaseF(int wv0, PP p, unsigned char* smem) {
;     ...
;             for (int j = 0; j < 4; ++j) acc[ai][0][m][n][j] *= sigmoidf_(acc[ai][1][m][n][j]);
;       __builtin_amdgcn_sched_barrier(0);
;       epi256(wv0, acc, brow, grp * 128, [&](int ai, int bj, int m, int n, int row, int col0, f32x4& v) {
;         if (bj == 0) {
;           const unsigned og = (unsigned)row * 2048u + 1024u + (unsigned)col0, om = (unsigned)row * 1024u + (unsigned)col0;
;           const uint2 gq = *(const uint2*)(MG + og);
;           *(uint2*)(MR + om) = pk4(__uint_as_float(gq.x << 16) * v[0], __uint_as_float(gq.x & 0xffff0000u) * v[1],
;                                    __uint_as_float(gq.y << 16) * v[2], __uint_as_float(gq.y & 0xffff0000u) * v[3]);
;         }
	v_mov_b32_e32 v58, v212
	v_mov_b32_e32 v59, v213
	v_lshlrev_b32_e32 v60, 16, v58
	v_and_b32_e32 v61, 0xffff0000, v58
	v_rcp_f32_e32 v58, v57
	s_nop 0
	v_fma_f32 v89, -v57, v58, 1.0
	v_fmac_f32_e32 v58, v89, v58
	v_div_scale_f32 v89, vcc, 1.0, v67, 1.0
	v_mul_f32_e32 v90, v89, v58
	v_fma_f32 v91, -v57, v90, v89
	v_fmac_f32_e32 v90, v91, v58
	v_fma_f32 v57, -v57, v90, v89
	v_div_fmas_f32 v57, v57, v58, v90
	v_div_fixup_f32 v67, v57, v67, 1.0
	v_div_scale_f32 v57, s[72:73], v66, v66, 1.0
	v_rcp_f32_e32 v58, v57
	s_nop 0
	v_fma_f32 v89, -v57, v58, 1.0
	v_fmac_f32_e32 v58, v89, v58
	v_div_scale_f32 v89, vcc, 1.0, v66, 1.0
	v_mul_f32_e32 v90, v89, v58
	v_fma_f32 v91, -v57, v90, v89
	v_fmac_f32_e32 v90, v91, v58
	v_fma_f32 v57, -v57, v90, v89
	v_div_fmas_f32 v57, v57, v58, v90
	v_div_fixup_f32 v66, v57, v66, 1.0
	v_pk_mul_f32 v[52:53], v[52:53], v[66:67]
	v_lshlrev_b32_e32 v58, 16, v59
	v_pk_mul_f32 v[52:53], v[52:53], v[60:61]
	v_pk_add_f32 v[60:61], v[138:139], 1.0 op_sel_hi:[1,0]
	v_and_b32_e32 v59, 0xffff0000, v59
	v_div_scale_f32 v57, s[72:73], v61, v61, 1.0
	v_rcp_f32_e32 v66, v57
	v_cvt_pk_bf16_f32 v52, v52, v53
	v_fma_f32 v67, -v57, v66, 1.0
	v_fmac_f32_e32 v66, v67, v66
	v_div_scale_f32 v67, vcc, 1.0, v61, 1.0
	v_mul_f32_e32 v89, v67, v66
	v_fma_f32 v90, -v57, v89, v67
	v_fmac_f32_e32 v89, v90, v66
	v_fma_f32 v57, -v57, v89, v67
	v_div_fmas_f32 v57, v57, v66, v89
	v_div_fixup_f32 v61, v57, v61, 1.0
	v_div_scale_f32 v57, s[72:73], v60, v60, 1.0
	v_rcp_f32_e32 v66, v57
	s_nop 0
	v_fma_f32 v67, -v57, v66, 1.0
	v_fmac_f32_e32 v66, v67, v66
	v_div_scale_f32 v67, vcc, 1.0, v60, 1.0
	v_mul_f32_e32 v89, v67, v66
	v_fma_f32 v90, -v57, v89, v67
	v_fmac_f32_e32 v89, v90, v66
	v_fma_f32 v57, -v57, v89, v67
	v_div_fmas_f32 v57, v57, v66, v89
	v_div_fixup_f32 v60, v57, v60, 1.0
	v_pk_mul_f32 v[54:55], v[54:55], v[60:61]
	v_mov_b32_e32 v57, v129
	v_pk_mul_f32 v[54:55], v[54:55], v[58:59]
	v_pk_add_f32 v[58:59], v[136:137], 1.0 op_sel_hi:[1,0]
	v_cvt_pk_bf16_f32 v53, v54, v55
	v_lshl_add_u64 v[54:55], v[56:57], 1, s[14:15]
	global_store_dwordx2 v[54:55], v[52:53], off
	v_lshl_add_u64 v[54:55], v[128:129], 1, s[12:13]
	v_div_scale_f32 v53, s[72:73], v59, v59, 1.0
	v_add_u32_e32 v52, v62, v88
	s_waitcnt vmcnt(15)
	v_mov_b32_e32 v54, v214
	v_mov_b32_e32 v55, v215
	v_lshlrev_b32_e32 v56, 16, v54
	v_and_b32_e32 v57, 0xffff0000, v54
	v_rcp_f32_e32 v54, v53
	s_nop 0
	v_fma_f32 v60, -v53, v54, 1.0
	v_fmac_f32_e32 v54, v60, v54
	v_div_scale_f32 v60, vcc, 1.0, v59, 1.0
	v_mul_f32_e32 v61, v60, v54
	v_fma_f32 v63, -v53, v61, v60
	v_fmac_f32_e32 v61, v63, v54
	v_fma_f32 v53, -v53, v61, v60
	v_div_fmas_f32 v53, v53, v54, v61
	v_div_fixup_f32 v59, v53, v59, 1.0
	v_div_scale_f32 v53, s[72:73], v58, v58, 1.0
	v_rcp_f32_e32 v54, v53
	s_nop 0
	v_fma_f32 v60, -v53, v54, 1.0
	v_fmac_f32_e32 v54, v60, v54
	v_div_scale_f32 v60, vcc, 1.0, v58, 1.0
	v_mul_f32_e32 v61, v60, v54
	v_fma_f32 v63, -v53, v61, v60
	v_fmac_f32_e32 v61, v63, v54
	v_fma_f32 v53, -v53, v61, v60
	v_div_fmas_f32 v53, v53, v54, v61
	v_div_fixup_f32 v58, v53, v58, 1.0
	v_pk_mul_f32 v[48:49], v[48:49], v[58:59]
	v_lshlrev_b32_e32 v54, 16, v55
	v_pk_mul_f32 v[48:49], v[48:49], v[56:57]
	v_pk_add_f32 v[56:57], v[134:135], 1.0 op_sel_hi:[1,0]
	v_and_b32_e32 v55, 0xffff0000, v55
	v_div_scale_f32 v53, s[72:73], v57, v57, 1.0
	v_rcp_f32_e32 v58, v53
	v_cvt_pk_bf16_f32 v48, v48, v49
	v_fma_f32 v59, -v53, v58, 1.0
	v_fmac_f32_e32 v58, v59, v58
	v_div_scale_f32 v59, vcc, 1.0, v57, 1.0
	v_mul_f32_e32 v60, v59, v58
	v_fma_f32 v61, -v53, v60, v59
	v_fmac_f32_e32 v60, v61, v58
	v_fma_f32 v53, -v53, v60, v59
	v_div_fmas_f32 v53, v53, v58, v60
	v_div_fixup_f32 v57, v53, v57, 1.0
	v_div_scale_f32 v53, s[72:73], v56, v56, 1.0
	v_rcp_f32_e32 v58, v53
	s_nop 0
	v_fma_f32 v59, -v53, v58, 1.0
	v_fmac_f32_e32 v58, v59, v58
	v_div_scale_f32 v59, vcc, 1.0, v56, 1.0
	v_mul_f32_e32 v60, v59, v58
	v_fma_f32 v61, -v53, v60, v59
	v_fmac_f32_e32 v60, v61, v58
	v_fma_f32 v53, -v53, v60, v59
	v_div_fmas_f32 v53, v53, v58, v60
	v_div_fixup_f32 v56, v53, v56, 1.0
	v_pk_mul_f32 v[50:51], v[50:51], v[56:57]
	v_mov_b32_e32 v53, v129
	v_pk_mul_f32 v[50:51], v[50:51], v[54:55]
	s_nop 0
	v_cvt_pk_bf16_f32 v49, v50, v51
	v_lshl_add_u64 v[50:51], v[52:53], 1, s[14:15]
	global_store_dwordx2 v[50:51], v[48:49], off
	v_or_b32_e32 v48, 32, v83
	v_lshl_or_b32 v56, v48, 11, v151
	v_or_b32_e32 v128, v56, v82
	v_lshl_add_u64 v[50:51], v[128:129], 1, s[12:13]
	v_pk_add_f32 v[54:55], v[132:133], 1.0 op_sel_hi:[1,0]
	v_lshlrev_b32_e32 v57, 10, v48
	v_div_scale_f32 v49, s[72:73], v55, v55, 1.0
	v_or_b32_e32 v48, v57, v82
	v_add_u32_e32 v128, v56, v62
	s_waitcnt vmcnt(15)
; DI uint2 pk4(float a, float b, float c, float d) { uint2 o; o.x = pk2(a, b); o.y = pk2(c, d); return o; }
; DI float sigmoidf_(float x) { return 1.f / (1.f + __expf(-x)); }
; DI void phaseF(int wv0, PP p, unsigned char* smem) {
;     ...
;             for (int j = 0; j < 4; ++j) acc[ai][0][m][n][j] *= sigmoidf_(acc[ai][1][m][n][j]);
;       __builtin_amdgcn_sched_barrier(0);
;       epi256(wv0, acc, brow, grp * 128, [&](int ai, int bj, int m, int n, int row, int col0, f32x4& v) {
;         if (bj == 0) {
;           const unsigned og = (unsigned)row * 2048u + 1024u + (unsigned)col0, om = (unsigned)row * 1024u + (unsigned)col0;
;           const uint2 gq = *(const uint2*)(MG + og);
;           *(uint2*)(MR + om) = pk4(__uint_as_float(gq.x << 16) * v[0], __uint_as_float(gq.x & 0xffff0000u) * v[1],
;                                    __uint_as_float(gq.y << 16) * v[2], __uint_as_float(gq.y & 0xffff0000u) * v[3]);
;         }
	v_mov_b32_e32 v50, v216
	v_mov_b32_e32 v51, v217
	v_lshlrev_b32_e32 v52, 16, v50
	v_and_b32_e32 v53, 0xffff0000, v50
	v_rcp_f32_e32 v50, v49
	s_nop 0
	v_fma_f32 v58, -v49, v50, 1.0
	v_fmac_f32_e32 v50, v58, v50
	v_div_scale_f32 v58, vcc, 1.0, v55, 1.0
	v_mul_f32_e32 v59, v58, v50
	v_fma_f32 v60, -v49, v59, v58
	v_fmac_f32_e32 v59, v60, v50
	v_fma_f32 v49, -v49, v59, v58
	v_div_fmas_f32 v49, v49, v50, v59
	v_div_fixup_f32 v55, v49, v55, 1.0
	v_div_scale_f32 v49, s[72:73], v54, v54, 1.0
	v_rcp_f32_e32 v50, v49
	s_nop 0
	v_fma_f32 v58, -v49, v50, 1.0
	v_fmac_f32_e32 v50, v58, v50
	v_div_scale_f32 v58, vcc, 1.0, v54, 1.0
	v_mul_f32_e32 v59, v58, v50
	v_fma_f32 v60, -v49, v59, v58
	v_fmac_f32_e32 v59, v60, v50
	v_fma_f32 v49, -v49, v59, v58
	v_div_fmas_f32 v49, v49, v50, v59
	v_div_fixup_f32 v54, v49, v54, 1.0
	v_pk_mul_f32 v[44:45], v[44:45], v[54:55]
	v_lshlrev_b32_e32 v50, 16, v51
	v_pk_mul_f32 v[44:45], v[44:45], v[52:53]
	v_pk_add_f32 v[52:53], v[130:131], 1.0 op_sel_hi:[1,0]
	v_and_b32_e32 v51, 0xffff0000, v51
	v_div_scale_f32 v49, s[72:73], v53, v53, 1.0
	v_rcp_f32_e32 v54, v49
	v_cvt_pk_bf16_f32 v44, v44, v45
	v_fma_f32 v55, -v49, v54, 1.0
	v_fmac_f32_e32 v54, v55, v54
	v_div_scale_f32 v55, vcc, 1.0, v53, 1.0
	v_mul_f32_e32 v58, v55, v54
	v_fma_f32 v59, -v49, v58, v55
	v_fmac_f32_e32 v58, v59, v54
	v_fma_f32 v49, -v49, v58, v55
	v_div_fmas_f32 v49, v49, v54, v58
	v_div_fixup_f32 v53, v49, v53, 1.0
	v_div_scale_f32 v49, s[72:73], v52, v52, 1.0
	v_rcp_f32_e32 v54, v49
	s_nop 0
	v_fma_f32 v55, -v49, v54, 1.0
	v_fmac_f32_e32 v54, v55, v54
	v_div_scale_f32 v55, vcc, 1.0, v52, 1.0
	v_mul_f32_e32 v58, v55, v54
	v_fma_f32 v59, -v49, v58, v55
	v_fmac_f32_e32 v58, v59, v54
	v_fma_f32 v49, -v49, v58, v55
	v_div_fmas_f32 v49, v49, v54, v58
	v_div_fixup_f32 v52, v49, v52, 1.0
	v_pk_mul_f32 v[46:47], v[46:47], v[52:53]
	v_mov_b32_e32 v49, v129
	v_pk_mul_f32 v[46:47], v[46:47], v[50:51]
	v_pk_add_f32 v[50:51], v[126:127], 1.0 op_sel_hi:[1,0]
	v_cvt_pk_bf16_f32 v45, v46, v47
	v_lshl_add_u64 v[46:47], v[48:49], 1, s[14:15]
	global_store_dwordx2 v[46:47], v[44:45], off
	v_lshl_add_u64 v[46:47], v[128:129], 1, s[12:13]
	v_div_scale_f32 v45, s[72:73], v51, v51, 1.0
	v_add_u32_e32 v44, v62, v57
	s_waitcnt vmcnt(15)
	v_mov_b32_e32 v46, v218
	v_mov_b32_e32 v47, v219
	v_lshlrev_b32_e32 v48, 16, v46
	v_and_b32_e32 v49, 0xffff0000, v46
	v_rcp_f32_e32 v46, v45
	s_nop 0
	v_fma_f32 v52, -v45, v46, 1.0
	v_fmac_f32_e32 v46, v52, v46
	v_div_scale_f32 v52, vcc, 1.0, v51, 1.0
	v_mul_f32_e32 v53, v52, v46
	v_fma_f32 v54, -v45, v53, v52
	v_fmac_f32_e32 v53, v54, v46
	v_fma_f32 v45, -v45, v53, v52
	v_div_fmas_f32 v45, v45, v46, v53
	v_div_fixup_f32 v51, v45, v51, 1.0
	v_div_scale_f32 v45, s[72:73], v50, v50, 1.0
	v_rcp_f32_e32 v46, v45
	s_nop 0
	v_fma_f32 v52, -v45, v46, 1.0
	v_fmac_f32_e32 v46, v52, v46
	v_div_scale_f32 v52, vcc, 1.0, v50, 1.0
	v_mul_f32_e32 v53, v52, v46
	v_fma_f32 v54, -v45, v53, v52
	v_fmac_f32_e32 v53, v54, v46
	v_fma_f32 v45, -v45, v53, v52
	v_div_fmas_f32 v45, v45, v46, v53
	v_div_fixup_f32 v50, v45, v50, 1.0
	v_pk_mul_f32 v[40:41], v[40:41], v[50:51]
	v_lshlrev_b32_e32 v46, 16, v47
	v_pk_mul_f32 v[40:41], v[40:41], v[48:49]
	v_pk_add_f32 v[48:49], v[124:125], 1.0 op_sel_hi:[1,0]
	v_and_b32_e32 v47, 0xffff0000, v47
	v_div_scale_f32 v45, s[72:73], v49, v49, 1.0
	v_rcp_f32_e32 v50, v45
	v_cvt_pk_bf16_f32 v40, v40, v41
	v_fma_f32 v51, -v45, v50, 1.0
	v_fmac_f32_e32 v50, v51, v50
	v_div_scale_f32 v51, vcc, 1.0, v49, 1.0
	v_mul_f32_e32 v52, v51, v50
	v_fma_f32 v53, -v45, v52, v51
	v_fmac_f32_e32 v52, v53, v50
	v_fma_f32 v45, -v45, v52, v51
	v_div_fmas_f32 v45, v45, v50, v52
	v_div_fixup_f32 v49, v45, v49, 1.0
	v_div_scale_f32 v45, s[72:73], v48, v48, 1.0
	v_rcp_f32_e32 v50, v45
	s_nop 0
	v_fma_f32 v51, -v45, v50, 1.0
	v_fmac_f32_e32 v50, v51, v50
	v_div_scale_f32 v51, vcc, 1.0, v48, 1.0
	v_mul_f32_e32 v52, v51, v50
	v_fma_f32 v53, -v45, v52, v51
	v_fmac_f32_e32 v52, v53, v50
	v_fma_f32 v45, -v45, v52, v51
	v_div_fmas_f32 v45, v45, v50, v52
	v_div_fixup_f32 v48, v45, v48, 1.0
	v_pk_mul_f32 v[42:43], v[42:43], v[48:49]
	v_mov_b32_e32 v45, v129
	v_pk_mul_f32 v[42:43], v[42:43], v[46:47]
	v_pk_add_f32 v[46:47], v[122:123], 1.0 op_sel_hi:[1,0]
	v_cvt_pk_bf16_f32 v41, v42, v43
	v_lshl_add_u64 v[42:43], v[44:45], 1, s[14:15]
	global_store_dwordx2 v[42:43], v[40:41], off
	v_or_b32_e32 v40, 48, v83
	v_lshl_or_b32 v48, v40, 11, v151
	v_or_b32_e32 v128, v48, v82
	v_lshl_add_u64 v[42:43], v[128:129], 1, s[12:13]
	v_div_scale_f32 v41, s[72:73], v47, v47, 1.0
	v_lshlrev_b32_e32 v49, 10, v40
	v_or_b32_e32 v40, v49, v82
	v_add_u32_e32 v128, v48, v62
	s_waitcnt vmcnt(15)
; DI uint2 pk4(float a, float b, float c, float d) { uint2 o; o.x = pk2(a, b); o.y = pk2(c, d); return o; }
; DI float sigmoidf_(float x) { return 1.f / (1.f + __expf(-x)); }
; DI void phaseF(int wv0, PP p, unsigned char* smem) {
;     ...
;             for (int j = 0; j < 4; ++j) acc[ai][0][m][n][j] *= sigmoidf_(acc[ai][1][m][n][j]);
;       __builtin_amdgcn_sched_barrier(0);
;       epi256(wv0, acc, brow, grp * 128, [&](int ai, int bj, int m, int n, int row, int col0, f32x4& v) {
;         if (bj == 0) {
;           const unsigned og = (unsigned)row * 2048u + 1024u + (unsigned)col0, om = (unsigned)row * 1024u + (unsigned)col0;
;           const uint2 gq = *(const uint2*)(MG + og);
;           *(uint2*)(MR + om) = pk4(__uint_as_float(gq.x << 16) * v[0], __uint_as_float(gq.x & 0xffff0000u) * v[1],
;                                    __uint_as_float(gq.y << 16) * v[2], __uint_as_float(gq.y & 0xffff0000u) * v[3]);
;         }
	v_mov_b32_e32 v42, v220
	v_mov_b32_e32 v43, v221
	v_lshlrev_b32_e32 v44, 16, v42
	v_and_b32_e32 v45, 0xffff0000, v42
	v_rcp_f32_e32 v42, v41
	s_nop 0
	v_fma_f32 v50, -v41, v42, 1.0
	v_fmac_f32_e32 v42, v50, v42
	v_div_scale_f32 v50, vcc, 1.0, v47, 1.0
	v_mul_f32_e32 v51, v50, v42
	v_fma_f32 v52, -v41, v51, v50
	v_fmac_f32_e32 v51, v52, v42
	v_fma_f32 v41, -v41, v51, v50
	v_div_fmas_f32 v41, v41, v42, v51
	v_div_fixup_f32 v47, v41, v47, 1.0
	v_div_scale_f32 v41, s[72:73], v46, v46, 1.0
	v_rcp_f32_e32 v42, v41
	s_nop 0
	v_fma_f32 v50, -v41, v42, 1.0
	v_fmac_f32_e32 v42, v50, v42
	v_div_scale_f32 v50, vcc, 1.0, v46, 1.0
	v_mul_f32_e32 v51, v50, v42
	v_fma_f32 v52, -v41, v51, v50
	v_fmac_f32_e32 v51, v52, v42
	v_fma_f32 v41, -v41, v51, v50
	v_div_fmas_f32 v41, v41, v42, v51
	v_div_fixup_f32 v46, v41, v46, 1.0
	v_pk_mul_f32 v[36:37], v[36:37], v[46:47]
	v_lshlrev_b32_e32 v42, 16, v43
	v_pk_mul_f32 v[36:37], v[36:37], v[44:45]
	v_pk_add_f32 v[44:45], v[120:121], 1.0 op_sel_hi:[1,0]
	v_and_b32_e32 v43, 0xffff0000, v43
	v_div_scale_f32 v41, s[72:73], v45, v45, 1.0
	v_rcp_f32_e32 v46, v41
	v_cvt_pk_bf16_f32 v36, v36, v37
	v_fma_f32 v47, -v41, v46, 1.0
	v_fmac_f32_e32 v46, v47, v46
	v_div_scale_f32 v47, vcc, 1.0, v45, 1.0
	v_mul_f32_e32 v50, v47, v46
	v_fma_f32 v51, -v41, v50, v47
	v_fmac_f32_e32 v50, v51, v46
	v_fma_f32 v41, -v41, v50, v47
	v_div_fmas_f32 v41, v41, v46, v50
	v_div_fixup_f32 v45, v41, v45, 1.0
	v_div_scale_f32 v41, s[72:73], v44, v44, 1.0
	v_rcp_f32_e32 v46, v41
	s_nop 0
	v_fma_f32 v47, -v41, v46, 1.0
	v_fmac_f32_e32 v46, v47, v46
	v_div_scale_f32 v47, vcc, 1.0, v44, 1.0
	v_mul_f32_e32 v50, v47, v46
	v_fma_f32 v51, -v41, v50, v47
	v_fmac_f32_e32 v50, v51, v46
	v_fma_f32 v41, -v41, v50, v47
	v_div_fmas_f32 v41, v41, v46, v50
	v_div_fixup_f32 v44, v41, v44, 1.0
	v_pk_mul_f32 v[38:39], v[38:39], v[44:45]
	v_mov_b32_e32 v41, v129
	v_pk_mul_f32 v[38:39], v[38:39], v[42:43]
	v_pk_add_f32 v[42:43], v[118:119], 1.0 op_sel_hi:[1,0]
	v_cvt_pk_bf16_f32 v37, v38, v39
	v_lshl_add_u64 v[38:39], v[40:41], 1, s[14:15]
	global_store_dwordx2 v[38:39], v[36:37], off
	v_lshl_add_u64 v[38:39], v[128:129], 1, s[12:13]
	v_div_scale_f32 v37, s[72:73], v43, v43, 1.0
	v_add_u32_e32 v36, v62, v49
	s_waitcnt vmcnt(15)
	v_mov_b32_e32 v38, v222
	v_mov_b32_e32 v39, v223
	v_lshlrev_b32_e32 v40, 16, v38
	v_and_b32_e32 v41, 0xffff0000, v38
	v_rcp_f32_e32 v38, v37
	s_nop 0
	v_fma_f32 v44, -v37, v38, 1.0
	v_fmac_f32_e32 v38, v44, v38
	v_div_scale_f32 v44, vcc, 1.0, v43, 1.0
	v_mul_f32_e32 v45, v44, v38
	v_fma_f32 v46, -v37, v45, v44
	v_fmac_f32_e32 v45, v46, v38
	v_fma_f32 v37, -v37, v45, v44
	v_div_fmas_f32 v37, v37, v38, v45
	v_div_fixup_f32 v43, v37, v43, 1.0
	v_div_scale_f32 v37, s[72:73], v42, v42, 1.0
	v_rcp_f32_e32 v38, v37
	s_nop 0
	v_fma_f32 v44, -v37, v38, 1.0
	v_fmac_f32_e32 v38, v44, v38
	v_div_scale_f32 v44, vcc, 1.0, v42, 1.0
	v_mul_f32_e32 v45, v44, v38
	v_fma_f32 v46, -v37, v45, v44
	v_fmac_f32_e32 v45, v46, v38
	v_fma_f32 v37, -v37, v45, v44
	v_div_fmas_f32 v37, v37, v38, v45
	v_div_fixup_f32 v42, v37, v42, 1.0
	v_pk_mul_f32 v[32:33], v[32:33], v[42:43]
	v_lshlrev_b32_e32 v38, 16, v39
	v_pk_mul_f32 v[32:33], v[32:33], v[40:41]
	v_pk_add_f32 v[40:41], v[116:117], 1.0 op_sel_hi:[1,0]
	v_and_b32_e32 v39, 0xffff0000, v39
	v_div_scale_f32 v37, s[72:73], v41, v41, 1.0
	v_rcp_f32_e32 v42, v37
	v_cvt_pk_bf16_f32 v32, v32, v33
	v_fma_f32 v43, -v37, v42, 1.0
	v_fmac_f32_e32 v42, v43, v42
	v_div_scale_f32 v43, vcc, 1.0, v41, 1.0
	v_mul_f32_e32 v44, v43, v42
	v_fma_f32 v45, -v37, v44, v43
	v_fmac_f32_e32 v44, v45, v42
	v_fma_f32 v37, -v37, v44, v43
	v_div_fmas_f32 v37, v37, v42, v44
	v_div_fixup_f32 v41, v37, v41, 1.0
	v_div_scale_f32 v37, s[72:73], v40, v40, 1.0
	v_rcp_f32_e32 v42, v37
	s_nop 0
	v_fma_f32 v43, -v37, v42, 1.0
	v_fmac_f32_e32 v42, v43, v42
	v_div_scale_f32 v43, vcc, 1.0, v40, 1.0
	v_mul_f32_e32 v44, v43, v42
	v_fma_f32 v45, -v37, v44, v43
	v_fmac_f32_e32 v44, v45, v42
	v_fma_f32 v37, -v37, v44, v43
	v_div_fmas_f32 v37, v37, v42, v44
	v_div_fixup_f32 v40, v37, v40, 1.0
	v_pk_mul_f32 v[34:35], v[34:35], v[40:41]
	v_mov_b32_e32 v37, v129
	v_pk_mul_f32 v[34:35], v[34:35], v[38:39]
	s_nop 0
	v_cvt_pk_bf16_f32 v33, v34, v35
	v_lshl_add_u64 v[34:35], v[36:37], 1, s[14:15]
	global_store_dwordx2 v[34:35], v[32:33], off
	v_add_u32_e32 v32, 0x80, v83
	v_lshl_or_b32 v40, v32, 11, v151
	v_or_b32_e32 v128, v40, v82
	v_lshl_add_u64 v[34:35], v[128:129], 1, s[12:13]
	v_pk_add_f32 v[38:39], v[110:111], 1.0 op_sel_hi:[1,0]
	v_lshlrev_b32_e32 v41, 10, v32
	v_div_scale_f32 v33, s[72:73], v39, v39, 1.0
	v_or_b32_e32 v32, v41, v82
	v_add_u32_e32 v128, v40, v62
	s_waitcnt vmcnt(15)
; DI uint2 pk4(float a, float b, float c, float d) { uint2 o; o.x = pk2(a, b); o.y = pk2(c, d); return o; }
; DI float sigmoidf_(float x) { return 1.f / (1.f + __expf(-x)); }
; DI void phaseF(int wv0, PP p, unsigned char* smem) {
;     ...
;             for (int j = 0; j < 4; ++j) acc[ai][0][m][n][j] *= sigmoidf_(acc[ai][1][m][n][j]);
;       __builtin_amdgcn_sched_barrier(0);
;       epi256(wv0, acc, brow, grp * 128, [&](int ai, int bj, int m, int n, int row, int col0, f32x4& v) {
;         if (bj == 0) {
;           const unsigned og = (unsigned)row * 2048u + 1024u + (unsigned)col0, om = (unsigned)row * 1024u + (unsigned)col0;
;           const uint2 gq = *(const uint2*)(MG + og);
;           *(uint2*)(MR + om) = pk4(__uint_as_float(gq.x << 16) * v[0], __uint_as_float(gq.x & 0xffff0000u) * v[1],
;                                    __uint_as_float(gq.y << 16) * v[2], __uint_as_float(gq.y & 0xffff0000u) * v[3]);
;         }
	v_mov_b32_e32 v34, v224
	v_mov_b32_e32 v35, v225
	v_lshlrev_b32_e32 v36, 16, v34
	v_and_b32_e32 v37, 0xffff0000, v34
	v_rcp_f32_e32 v34, v33
	s_nop 0
	v_fma_f32 v42, -v33, v34, 1.0
	v_fmac_f32_e32 v34, v42, v34
	v_div_scale_f32 v42, vcc, 1.0, v39, 1.0
	v_mul_f32_e32 v43, v42, v34
	v_fma_f32 v44, -v33, v43, v42
	v_fmac_f32_e32 v43, v44, v34
	v_fma_f32 v33, -v33, v43, v42
	v_div_fmas_f32 v33, v33, v34, v43
	v_div_fixup_f32 v39, v33, v39, 1.0
	v_div_scale_f32 v33, s[72:73], v38, v38, 1.0
	v_rcp_f32_e32 v34, v33
	s_nop 0
	v_fma_f32 v42, -v33, v34, 1.0
	v_fmac_f32_e32 v34, v42, v34
	v_div_scale_f32 v42, vcc, 1.0, v38, 1.0
	v_mul_f32_e32 v43, v42, v34
	v_fma_f32 v44, -v33, v43, v42
	v_fmac_f32_e32 v43, v44, v34
	v_fma_f32 v33, -v33, v43, v42
	v_div_fmas_f32 v33, v33, v34, v43
	v_div_fixup_f32 v38, v33, v38, 1.0
	v_pk_mul_f32 v[28:29], v[28:29], v[38:39]
	v_lshlrev_b32_e32 v34, 16, v35
	v_pk_mul_f32 v[28:29], v[28:29], v[36:37]
	v_pk_add_f32 v[36:37], v[108:109], 1.0 op_sel_hi:[1,0]
	v_and_b32_e32 v35, 0xffff0000, v35
	v_div_scale_f32 v33, s[72:73], v37, v37, 1.0
	v_rcp_f32_e32 v38, v33
	v_cvt_pk_bf16_f32 v28, v28, v29
	v_fma_f32 v39, -v33, v38, 1.0
	v_fmac_f32_e32 v38, v39, v38
	v_div_scale_f32 v39, vcc, 1.0, v37, 1.0
	v_mul_f32_e32 v42, v39, v38
	v_fma_f32 v43, -v33, v42, v39
	v_fmac_f32_e32 v42, v43, v38
	v_fma_f32 v33, -v33, v42, v39
	v_div_fmas_f32 v33, v33, v38, v42
	v_div_fixup_f32 v37, v33, v37, 1.0
	v_div_scale_f32 v33, s[72:73], v36, v36, 1.0
	v_rcp_f32_e32 v38, v33
	s_nop 0
	v_fma_f32 v39, -v33, v38, 1.0
	v_fmac_f32_e32 v38, v39, v38
	v_div_scale_f32 v39, vcc, 1.0, v36, 1.0
	v_mul_f32_e32 v42, v39, v38
	v_fma_f32 v43, -v33, v42, v39
	v_fmac_f32_e32 v42, v43, v38
	v_fma_f32 v33, -v33, v42, v39
	v_div_fmas_f32 v33, v33, v38, v42
	v_div_fixup_f32 v36, v33, v36, 1.0
	v_pk_mul_f32 v[30:31], v[30:31], v[36:37]
	v_mov_b32_e32 v33, v129
	v_pk_mul_f32 v[30:31], v[30:31], v[34:35]
	v_pk_add_f32 v[34:35], v[102:103], 1.0 op_sel_hi:[1,0]
	v_cvt_pk_bf16_f32 v29, v30, v31
	v_lshl_add_u64 v[30:31], v[32:33], 1, s[14:15]
	global_store_dwordx2 v[30:31], v[28:29], off
	v_lshl_add_u64 v[30:31], v[128:129], 1, s[12:13]
	v_div_scale_f32 v29, s[72:73], v35, v35, 1.0
	v_add_u32_e32 v28, v62, v41
	s_waitcnt vmcnt(15)
	v_mov_b32_e32 v30, v226
	v_mov_b32_e32 v31, v227
	v_lshlrev_b32_e32 v32, 16, v30
	v_and_b32_e32 v33, 0xffff0000, v30
	v_rcp_f32_e32 v30, v29
	s_nop 0
	v_fma_f32 v36, -v29, v30, 1.0
	v_fmac_f32_e32 v30, v36, v30
	v_div_scale_f32 v36, vcc, 1.0, v35, 1.0
	v_mul_f32_e32 v37, v36, v30
	v_fma_f32 v38, -v29, v37, v36
	v_fmac_f32_e32 v37, v38, v30
	v_fma_f32 v29, -v29, v37, v36
	v_div_fmas_f32 v29, v29, v30, v37
	v_div_fixup_f32 v35, v29, v35, 1.0
	v_div_scale_f32 v29, s[72:73], v34, v34, 1.0
	v_rcp_f32_e32 v30, v29
	s_nop 0
	v_fma_f32 v36, -v29, v30, 1.0
	v_fmac_f32_e32 v30, v36, v30
	v_div_scale_f32 v36, vcc, 1.0, v34, 1.0
	v_mul_f32_e32 v37, v36, v30
	v_fma_f32 v38, -v29, v37, v36
	v_fmac_f32_e32 v37, v38, v30
	v_fma_f32 v29, -v29, v37, v36
	v_div_fmas_f32 v29, v29, v30, v37
	v_div_fixup_f32 v34, v29, v34, 1.0
	v_pk_mul_f32 v[24:25], v[24:25], v[34:35]
	v_lshlrev_b32_e32 v30, 16, v31
	v_pk_mul_f32 v[24:25], v[24:25], v[32:33]
	v_pk_add_f32 v[32:33], v[100:101], 1.0 op_sel_hi:[1,0]
	v_and_b32_e32 v31, 0xffff0000, v31
	v_div_scale_f32 v29, s[72:73], v33, v33, 1.0
	v_rcp_f32_e32 v34, v29
	v_cvt_pk_bf16_f32 v24, v24, v25
	v_fma_f32 v35, -v29, v34, 1.0
	v_fmac_f32_e32 v34, v35, v34
	v_div_scale_f32 v35, vcc, 1.0, v33, 1.0
	v_mul_f32_e32 v36, v35, v34
	v_fma_f32 v37, -v29, v36, v35
	v_fmac_f32_e32 v36, v37, v34
	v_fma_f32 v29, -v29, v36, v35
	v_div_fmas_f32 v29, v29, v34, v36
	v_div_fixup_f32 v33, v29, v33, 1.0
	v_div_scale_f32 v29, s[72:73], v32, v32, 1.0
	v_rcp_f32_e32 v34, v29
	s_nop 0
	v_fma_f32 v35, -v29, v34, 1.0
	v_fmac_f32_e32 v34, v35, v34
	v_div_scale_f32 v35, vcc, 1.0, v32, 1.0
	v_mul_f32_e32 v36, v35, v34
	v_fma_f32 v37, -v29, v36, v35
	v_fmac_f32_e32 v36, v37, v34
	v_fma_f32 v29, -v29, v36, v35
	v_div_fmas_f32 v29, v29, v34, v36
	v_div_fixup_f32 v32, v29, v32, 1.0
	v_pk_mul_f32 v[26:27], v[26:27], v[32:33]
	v_mov_b32_e32 v29, v129
	v_pk_mul_f32 v[26:27], v[26:27], v[30:31]
	v_pk_add_f32 v[30:31], v[94:95], 1.0 op_sel_hi:[1,0]
	v_cvt_pk_bf16_f32 v25, v26, v27
	v_lshl_add_u64 v[26:27], v[28:29], 1, s[14:15]
	global_store_dwordx2 v[26:27], v[24:25], off
	v_add_u32_e32 v24, 0x90, v83
	v_lshl_or_b32 v32, v24, 11, v151
	v_or_b32_e32 v128, v32, v82
	v_lshl_add_u64 v[26:27], v[128:129], 1, s[12:13]
	v_div_scale_f32 v25, s[72:73], v31, v31, 1.0
	v_lshlrev_b32_e32 v33, 10, v24
	v_or_b32_e32 v24, v33, v82
	v_add_u32_e32 v128, v32, v62
	s_waitcnt vmcnt(15)
; DI uint2 pk4(float a, float b, float c, float d) { uint2 o; o.x = pk2(a, b); o.y = pk2(c, d); return o; }
; DI float sigmoidf_(float x) { return 1.f / (1.f + __expf(-x)); }
; DI void phaseF(int wv0, PP p, unsigned char* smem) {
;     ...
;             for (int j = 0; j < 4; ++j) acc[ai][0][m][n][j] *= sigmoidf_(acc[ai][1][m][n][j]);
;       __builtin_amdgcn_sched_barrier(0);
;       epi256(wv0, acc, brow, grp * 128, [&](int ai, int bj, int m, int n, int row, int col0, f32x4& v) {
;         if (bj == 0) {
;           const unsigned og = (unsigned)row * 2048u + 1024u + (unsigned)col0, om = (unsigned)row * 1024u + (unsigned)col0;
;           const uint2 gq = *(const uint2*)(MG + og);
;           *(uint2*)(MR + om) = pk4(__uint_as_float(gq.x << 16) * v[0], __uint_as_float(gq.x & 0xffff0000u) * v[1],
;                                    __uint_as_float(gq.y << 16) * v[2], __uint_as_float(gq.y & 0xffff0000u) * v[3]);
;         }
	v_mov_b32_e32 v26, v228
	v_mov_b32_e32 v27, v229
	v_lshlrev_b32_e32 v28, 16, v26
	v_and_b32_e32 v29, 0xffff0000, v26
	v_rcp_f32_e32 v26, v25
	s_nop 0
	v_fma_f32 v34, -v25, v26, 1.0
	v_fmac_f32_e32 v26, v34, v26
	v_div_scale_f32 v34, vcc, 1.0, v31, 1.0
	v_mul_f32_e32 v35, v34, v26
	v_fma_f32 v36, -v25, v35, v34
	v_fmac_f32_e32 v35, v36, v26
	v_fma_f32 v25, -v25, v35, v34
	v_div_fmas_f32 v25, v25, v26, v35
	v_div_fixup_f32 v31, v25, v31, 1.0
	v_div_scale_f32 v25, s[72:73], v30, v30, 1.0
	v_rcp_f32_e32 v26, v25
	s_nop 0
	v_fma_f32 v34, -v25, v26, 1.0
	v_fmac_f32_e32 v26, v34, v26
	v_div_scale_f32 v34, vcc, 1.0, v30, 1.0
	v_mul_f32_e32 v35, v34, v26
	v_fma_f32 v36, -v25, v35, v34
	v_fmac_f32_e32 v35, v36, v26
	v_fma_f32 v25, -v25, v35, v34
	v_div_fmas_f32 v25, v25, v26, v35
	v_div_fixup_f32 v30, v25, v30, 1.0
	v_pk_mul_f32 v[20:21], v[20:21], v[30:31]
	v_lshlrev_b32_e32 v26, 16, v27
	v_pk_mul_f32 v[20:21], v[20:21], v[28:29]
	v_pk_add_f32 v[28:29], v[92:93], 1.0 op_sel_hi:[1,0]
	v_and_b32_e32 v27, 0xffff0000, v27
	v_div_scale_f32 v25, s[72:73], v29, v29, 1.0
	v_rcp_f32_e32 v30, v25
	v_cvt_pk_bf16_f32 v20, v20, v21
	v_fma_f32 v31, -v25, v30, 1.0
	v_fmac_f32_e32 v30, v31, v30
	v_div_scale_f32 v31, vcc, 1.0, v29, 1.0
	v_mul_f32_e32 v34, v31, v30
	v_fma_f32 v35, -v25, v34, v31
	v_fmac_f32_e32 v34, v35, v30
	v_fma_f32 v25, -v25, v34, v31
	v_div_fmas_f32 v25, v25, v30, v34
	v_div_fixup_f32 v29, v25, v29, 1.0
	v_div_scale_f32 v25, s[72:73], v28, v28, 1.0
	v_rcp_f32_e32 v30, v25
	s_nop 0
	v_fma_f32 v31, -v25, v30, 1.0
	v_fmac_f32_e32 v30, v31, v30
	v_div_scale_f32 v31, vcc, 1.0, v28, 1.0
	v_mul_f32_e32 v34, v31, v30
	v_fma_f32 v35, -v25, v34, v31
	v_fmac_f32_e32 v34, v35, v30
	v_fma_f32 v25, -v25, v34, v31
	v_div_fmas_f32 v25, v25, v30, v34
	v_div_fixup_f32 v28, v25, v28, 1.0
	v_pk_mul_f32 v[22:23], v[22:23], v[28:29]
	v_mov_b32_e32 v25, v129
	v_pk_mul_f32 v[22:23], v[22:23], v[26:27]
	v_pk_add_f32 v[26:27], v[86:87], 1.0 op_sel_hi:[1,0]
	v_cvt_pk_bf16_f32 v21, v22, v23
	v_lshl_add_u64 v[22:23], v[24:25], 1, s[14:15]
	global_store_dwordx2 v[22:23], v[20:21], off
	v_lshl_add_u64 v[22:23], v[128:129], 1, s[12:13]
	v_div_scale_f32 v21, s[72:73], v27, v27, 1.0
	v_add_u32_e32 v20, v62, v33
	s_waitcnt vmcnt(15)
	v_mov_b32_e32 v22, v230
	v_mov_b32_e32 v23, v231
	v_lshlrev_b32_e32 v24, 16, v22
	v_and_b32_e32 v25, 0xffff0000, v22
	v_rcp_f32_e32 v22, v21
	s_nop 0
	v_fma_f32 v28, -v21, v22, 1.0
	v_fmac_f32_e32 v22, v28, v22
	v_div_scale_f32 v28, vcc, 1.0, v27, 1.0
	v_mul_f32_e32 v29, v28, v22
	v_fma_f32 v30, -v21, v29, v28
	v_fmac_f32_e32 v29, v30, v22
	v_fma_f32 v21, -v21, v29, v28
	v_div_fmas_f32 v21, v21, v22, v29
	v_div_fixup_f32 v27, v21, v27, 1.0
	v_div_scale_f32 v21, s[72:73], v26, v26, 1.0
	v_rcp_f32_e32 v22, v21
	s_nop 0
	v_fma_f32 v28, -v21, v22, 1.0
	v_fmac_f32_e32 v22, v28, v22
	v_div_scale_f32 v28, vcc, 1.0, v26, 1.0
	v_mul_f32_e32 v29, v28, v22
	v_fma_f32 v30, -v21, v29, v28
	v_fmac_f32_e32 v29, v30, v22
	v_fma_f32 v21, -v21, v29, v28
	v_div_fmas_f32 v21, v21, v22, v29
	v_div_fixup_f32 v26, v21, v26, 1.0
	v_pk_mul_f32 v[16:17], v[16:17], v[26:27]
	v_lshlrev_b32_e32 v22, 16, v23
	v_pk_mul_f32 v[16:17], v[16:17], v[24:25]
	v_pk_add_f32 v[24:25], v[84:85], 1.0 op_sel_hi:[1,0]
	v_and_b32_e32 v23, 0xffff0000, v23
	v_div_scale_f32 v21, s[72:73], v25, v25, 1.0
	v_rcp_f32_e32 v26, v21
	v_cvt_pk_bf16_f32 v16, v16, v17
	v_fma_f32 v27, -v21, v26, 1.0
	v_fmac_f32_e32 v26, v27, v26
	v_div_scale_f32 v27, vcc, 1.0, v25, 1.0
	v_mul_f32_e32 v28, v27, v26
	v_fma_f32 v29, -v21, v28, v27
	v_fmac_f32_e32 v28, v29, v26
	v_fma_f32 v21, -v21, v28, v27
	v_div_fmas_f32 v21, v21, v26, v28
	v_div_fixup_f32 v25, v21, v25, 1.0
	v_div_scale_f32 v21, s[72:73], v24, v24, 1.0
	v_rcp_f32_e32 v26, v21
	s_nop 0
	v_fma_f32 v27, -v21, v26, 1.0
	v_fmac_f32_e32 v26, v27, v26
	v_div_scale_f32 v27, vcc, 1.0, v24, 1.0
	v_mul_f32_e32 v28, v27, v26
	v_fma_f32 v29, -v21, v28, v27
	v_fmac_f32_e32 v28, v29, v26
	v_fma_f32 v21, -v21, v28, v27
	v_div_fmas_f32 v21, v21, v26, v28
	v_div_fixup_f32 v24, v21, v24, 1.0
	v_pk_mul_f32 v[18:19], v[18:19], v[24:25]
	v_mov_b32_e32 v21, v129
	v_pk_mul_f32 v[18:19], v[18:19], v[22:23]
	s_nop 0
	v_cvt_pk_bf16_f32 v17, v18, v19
	v_lshl_add_u64 v[18:19], v[20:21], 1, s[14:15]
	global_store_dwordx2 v[18:19], v[16:17], off
	v_add_u32_e32 v16, 0xa0, v83
	v_lshl_or_b32 v24, v16, 11, v151
	v_or_b32_e32 v128, v24, v82
	v_lshl_add_u64 v[18:19], v[128:129], 1, s[12:13]
	v_pk_add_f32 v[22:23], v[80:81], 1.0 op_sel_hi:[1,0]
	v_lshlrev_b32_e32 v25, 10, v16
	v_div_scale_f32 v17, s[72:73], v23, v23, 1.0
	v_or_b32_e32 v16, v25, v82
	v_add_u32_e32 v128, v24, v62
	s_waitcnt vmcnt(15)
; DI uint2 pk4(float a, float b, float c, float d) { uint2 o; o.x = pk2(a, b); o.y = pk2(c, d); return o; }
; DI float sigmoidf_(float x) { return 1.f / (1.f + __expf(-x)); }
; DI void phaseF(int wv0, PP p, unsigned char* smem) {
;     ...
;             for (int j = 0; j < 4; ++j) acc[ai][0][m][n][j] *= sigmoidf_(acc[ai][1][m][n][j]);
;       __builtin_amdgcn_sched_barrier(0);
;       epi256(wv0, acc, brow, grp * 128, [&](int ai, int bj, int m, int n, int row, int col0, f32x4& v) {
;         if (bj == 0) {
;           const unsigned og = (unsigned)row * 2048u + 1024u + (unsigned)col0, om = (unsigned)row * 1024u + (unsigned)col0;
;           const uint2 gq = *(const uint2*)(MG + og);
;           *(uint2*)(MR + om) = pk4(__uint_as_float(gq.x << 16) * v[0], __uint_as_float(gq.x & 0xffff0000u) * v[1],
;                                    __uint_as_float(gq.y << 16) * v[2], __uint_as_float(gq.y & 0xffff0000u) * v[3]);
;         }
	v_mov_b32_e32 v18, v232
	v_mov_b32_e32 v19, v233
	v_lshlrev_b32_e32 v20, 16, v18
	v_and_b32_e32 v21, 0xffff0000, v18
	v_rcp_f32_e32 v18, v17
	s_nop 0
	v_fma_f32 v26, -v17, v18, 1.0
	v_fmac_f32_e32 v18, v26, v18
	v_div_scale_f32 v26, vcc, 1.0, v23, 1.0
	v_mul_f32_e32 v27, v26, v18
	v_fma_f32 v28, -v17, v27, v26
	v_fmac_f32_e32 v27, v28, v18
	v_fma_f32 v17, -v17, v27, v26
	v_div_fmas_f32 v17, v17, v18, v27
	v_div_fixup_f32 v23, v17, v23, 1.0
	v_div_scale_f32 v17, s[72:73], v22, v22, 1.0
	v_rcp_f32_e32 v18, v17
	s_nop 0
	v_fma_f32 v26, -v17, v18, 1.0
	v_fmac_f32_e32 v18, v26, v18
	v_div_scale_f32 v26, vcc, 1.0, v22, 1.0
	v_mul_f32_e32 v27, v26, v18
	v_fma_f32 v28, -v17, v27, v26
	v_fmac_f32_e32 v27, v28, v18
	v_fma_f32 v17, -v17, v27, v26
	v_div_fmas_f32 v17, v17, v18, v27
	v_div_fixup_f32 v22, v17, v22, 1.0
	v_pk_mul_f32 v[12:13], v[12:13], v[22:23]
	v_lshlrev_b32_e32 v18, 16, v19
	v_pk_mul_f32 v[12:13], v[12:13], v[20:21]
	v_pk_add_f32 v[20:21], v[78:79], 1.0 op_sel_hi:[1,0]
	v_and_b32_e32 v19, 0xffff0000, v19
	v_div_scale_f32 v17, s[72:73], v21, v21, 1.0
	v_rcp_f32_e32 v22, v17
	v_cvt_pk_bf16_f32 v12, v12, v13
	v_fma_f32 v23, -v17, v22, 1.0
	v_fmac_f32_e32 v22, v23, v22
	v_div_scale_f32 v23, vcc, 1.0, v21, 1.0
	v_mul_f32_e32 v26, v23, v22
	v_fma_f32 v27, -v17, v26, v23
	v_fmac_f32_e32 v26, v27, v22
	v_fma_f32 v17, -v17, v26, v23
	v_div_fmas_f32 v17, v17, v22, v26
	v_div_fixup_f32 v21, v17, v21, 1.0
	v_div_scale_f32 v17, s[72:73], v20, v20, 1.0
	v_rcp_f32_e32 v22, v17
	s_nop 0
	v_fma_f32 v23, -v17, v22, 1.0
	v_fmac_f32_e32 v22, v23, v22
	v_div_scale_f32 v23, vcc, 1.0, v20, 1.0
	v_mul_f32_e32 v26, v23, v22
	v_fma_f32 v27, -v17, v26, v23
	v_fmac_f32_e32 v26, v27, v22
	v_fma_f32 v17, -v17, v26, v23
	v_div_fmas_f32 v17, v17, v22, v26
	v_div_fixup_f32 v20, v17, v20, 1.0
	v_pk_mul_f32 v[14:15], v[14:15], v[20:21]
	v_mov_b32_e32 v17, v129
	v_pk_mul_f32 v[14:15], v[14:15], v[18:19]
	v_pk_add_f32 v[18:19], v[76:77], 1.0 op_sel_hi:[1,0]
	v_cvt_pk_bf16_f32 v13, v14, v15
	v_lshl_add_u64 v[14:15], v[16:17], 1, s[14:15]
	global_store_dwordx2 v[14:15], v[12:13], off
	v_lshl_add_u64 v[14:15], v[128:129], 1, s[12:13]
	v_div_scale_f32 v13, s[72:73], v19, v19, 1.0
	v_add_u32_e32 v12, v62, v25
	s_waitcnt vmcnt(15)
	v_mov_b32_e32 v14, v234
	v_mov_b32_e32 v15, v235
	v_lshlrev_b32_e32 v16, 16, v14
	v_and_b32_e32 v17, 0xffff0000, v14
	v_rcp_f32_e32 v14, v13
	s_nop 0
	v_fma_f32 v20, -v13, v14, 1.0
	v_fmac_f32_e32 v14, v20, v14
	v_div_scale_f32 v20, vcc, 1.0, v19, 1.0
	v_mul_f32_e32 v21, v20, v14
	v_fma_f32 v22, -v13, v21, v20
	v_fmac_f32_e32 v21, v22, v14
	v_fma_f32 v13, -v13, v21, v20
	v_div_fmas_f32 v13, v13, v14, v21
	v_div_fixup_f32 v19, v13, v19, 1.0
	v_div_scale_f32 v13, s[72:73], v18, v18, 1.0
	v_rcp_f32_e32 v14, v13
	s_nop 0
	v_fma_f32 v20, -v13, v14, 1.0
	v_fmac_f32_e32 v14, v20, v14
	v_div_scale_f32 v20, vcc, 1.0, v18, 1.0
	v_mul_f32_e32 v21, v20, v14
	v_fma_f32 v22, -v13, v21, v20
	v_fmac_f32_e32 v21, v22, v14
	v_fma_f32 v13, -v13, v21, v20
	v_div_fmas_f32 v13, v13, v14, v21
	v_div_fixup_f32 v18, v13, v18, 1.0
	v_pk_mul_f32 v[8:9], v[8:9], v[18:19]
	v_lshlrev_b32_e32 v14, 16, v15
	v_pk_mul_f32 v[8:9], v[8:9], v[16:17]
	v_pk_add_f32 v[16:17], v[74:75], 1.0 op_sel_hi:[1,0]
	v_and_b32_e32 v15, 0xffff0000, v15
	v_div_scale_f32 v13, s[72:73], v17, v17, 1.0
	v_rcp_f32_e32 v18, v13
	v_cvt_pk_bf16_f32 v8, v8, v9
	v_fma_f32 v19, -v13, v18, 1.0
	v_fmac_f32_e32 v18, v19, v18
	v_div_scale_f32 v19, vcc, 1.0, v17, 1.0
	v_mul_f32_e32 v20, v19, v18
	v_fma_f32 v21, -v13, v20, v19
	v_fmac_f32_e32 v20, v21, v18
	v_fma_f32 v13, -v13, v20, v19
	v_div_fmas_f32 v13, v13, v18, v20
	v_div_fixup_f32 v17, v13, v17, 1.0
	v_div_scale_f32 v13, s[72:73], v16, v16, 1.0
	v_rcp_f32_e32 v18, v13
	s_nop 0
	v_fma_f32 v19, -v13, v18, 1.0
	v_fmac_f32_e32 v18, v19, v18
	v_div_scale_f32 v19, vcc, 1.0, v16, 1.0
	v_mul_f32_e32 v20, v19, v18
	v_fma_f32 v21, -v13, v20, v19
	v_fmac_f32_e32 v20, v21, v18
	v_fma_f32 v13, -v13, v20, v19
	v_div_fmas_f32 v13, v13, v18, v20
	v_div_fixup_f32 v16, v13, v16, 1.0
	v_pk_mul_f32 v[10:11], v[10:11], v[16:17]
	v_mov_b32_e32 v13, v129
	v_pk_mul_f32 v[10:11], v[10:11], v[14:15]
	v_pk_add_f32 v[14:15], v[72:73], 1.0 op_sel_hi:[1,0]
	v_cvt_pk_bf16_f32 v9, v10, v11
	v_lshl_add_u64 v[10:11], v[12:13], 1, s[14:15]
	global_store_dwordx2 v[10:11], v[8:9], off
	v_add_u32_e32 v8, 0xb0, v83
	v_lshl_or_b32 v16, v8, 11, v151
	v_or_b32_e32 v128, v16, v82
	v_lshl_add_u64 v[10:11], v[128:129], 1, s[12:13]
	v_div_scale_f32 v9, s[72:73], v15, v15, 1.0
	v_lshlrev_b32_e32 v17, 10, v8
	v_or_b32_e32 v8, v17, v82
	v_add_u32_e32 v128, v16, v62
	s_waitcnt vmcnt(15)
; DI uint2 pk4(float a, float b, float c, float d) { uint2 o; o.x = pk2(a, b); o.y = pk2(c, d); return o; }
; DI float sigmoidf_(float x) { return 1.f / (1.f + __expf(-x)); }
; DI void phaseF(int wv0, PP p, unsigned char* smem) {
;     ...
;             for (int j = 0; j < 4; ++j) acc[ai][0][m][n][j] *= sigmoidf_(acc[ai][1][m][n][j]);
;       __builtin_amdgcn_sched_barrier(0);
;       epi256(wv0, acc, brow, grp * 128, [&](int ai, int bj, int m, int n, int row, int col0, f32x4& v) {
;         if (bj == 0) {
;           const unsigned og = (unsigned)row * 2048u + 1024u + (unsigned)col0, om = (unsigned)row * 1024u + (unsigned)col0;
;           const uint2 gq = *(const uint2*)(MG + og);
;           *(uint2*)(MR + om) = pk4(__uint_as_float(gq.x << 16) * v[0], __uint_as_float(gq.x & 0xffff0000u) * v[1],
;                                    __uint_as_float(gq.y << 16) * v[2], __uint_as_float(gq.y & 0xffff0000u) * v[3]);
;         }
;       });
	v_mov_b32_e32 v10, v236
	v_mov_b32_e32 v11, v237
	v_lshlrev_b32_e32 v12, 16, v10
	v_and_b32_e32 v13, 0xffff0000, v10
	v_rcp_f32_e32 v10, v9
	s_nop 0
	v_fma_f32 v18, -v9, v10, 1.0
	v_fmac_f32_e32 v10, v18, v10
	v_div_scale_f32 v18, vcc, 1.0, v15, 1.0
	v_mul_f32_e32 v19, v18, v10
	v_fma_f32 v20, -v9, v19, v18
	v_fmac_f32_e32 v19, v20, v10
	v_fma_f32 v9, -v9, v19, v18
	v_div_fmas_f32 v9, v9, v10, v19
	v_div_fixup_f32 v15, v9, v15, 1.0
	v_div_scale_f32 v9, s[72:73], v14, v14, 1.0
	v_rcp_f32_e32 v10, v9
	s_nop 0
	v_fma_f32 v18, -v9, v10, 1.0
	v_fmac_f32_e32 v10, v18, v10
	v_div_scale_f32 v18, vcc, 1.0, v14, 1.0
	v_mul_f32_e32 v19, v18, v10
	v_fma_f32 v20, -v9, v19, v18
	v_fmac_f32_e32 v19, v20, v10
	v_fma_f32 v9, -v9, v19, v18
	v_div_fmas_f32 v9, v9, v10, v19
	v_div_fixup_f32 v14, v9, v14, 1.0
	v_pk_mul_f32 v[4:5], v[4:5], v[14:15]
	v_lshlrev_b32_e32 v10, 16, v11
	v_pk_mul_f32 v[4:5], v[4:5], v[12:13]
	v_pk_add_f32 v[12:13], v[70:71], 1.0 op_sel_hi:[1,0]
	v_and_b32_e32 v11, 0xffff0000, v11
	v_div_scale_f32 v9, s[72:73], v13, v13, 1.0
	v_rcp_f32_e32 v14, v9
	v_cvt_pk_bf16_f32 v4, v4, v5
	v_fma_f32 v15, -v9, v14, 1.0
	v_fmac_f32_e32 v14, v15, v14
	v_div_scale_f32 v15, vcc, 1.0, v13, 1.0
	v_mul_f32_e32 v18, v15, v14
	v_fma_f32 v19, -v9, v18, v15
	v_fmac_f32_e32 v18, v19, v14
	v_fma_f32 v9, -v9, v18, v15
	v_div_fmas_f32 v9, v9, v14, v18
	v_div_fixup_f32 v13, v9, v13, 1.0
	v_div_scale_f32 v9, s[72:73], v12, v12, 1.0
	v_rcp_f32_e32 v14, v9
	s_nop 0
	v_fma_f32 v15, -v9, v14, 1.0
	v_fmac_f32_e32 v14, v15, v14
	v_div_scale_f32 v15, vcc, 1.0, v12, 1.0
	v_mul_f32_e32 v18, v15, v14
	v_fma_f32 v19, -v9, v18, v15
	v_fmac_f32_e32 v18, v19, v14
	v_fma_f32 v9, -v9, v18, v15
	v_div_fmas_f32 v9, v9, v14, v18
	v_div_fixup_f32 v12, v9, v12, 1.0
	v_pk_mul_f32 v[6:7], v[6:7], v[12:13]
	v_mov_b32_e32 v9, v129
	v_pk_mul_f32 v[6:7], v[6:7], v[10:11]
	v_pk_add_f32 v[10:11], v[68:69], 1.0 op_sel_hi:[1,0]
	v_cvt_pk_bf16_f32 v5, v6, v7
	v_lshl_add_u64 v[6:7], v[8:9], 1, s[14:15]
	global_store_dwordx2 v[6:7], v[4:5], off
	v_lshl_add_u64 v[6:7], v[128:129], 1, s[12:13]
	v_div_scale_f32 v5, s[72:73], v11, v11, 1.0
	v_add_u32_e32 v4, v62, v17
	s_waitcnt vmcnt(15)
	v_mov_b32_e32 v6, v238
	v_mov_b32_e32 v7, v239
	v_lshlrev_b32_e32 v8, 16, v6
	v_and_b32_e32 v9, 0xffff0000, v6
	v_rcp_f32_e32 v6, v5
	s_nop 0
	v_fma_f32 v12, -v5, v6, 1.0
	v_fmac_f32_e32 v6, v12, v6
	v_div_scale_f32 v12, vcc, 1.0, v11, 1.0
	v_mul_f32_e32 v13, v12, v6
	v_fma_f32 v14, -v5, v13, v12
	v_fmac_f32_e32 v13, v14, v6
	v_fma_f32 v5, -v5, v13, v12
	v_div_fmas_f32 v5, v5, v6, v13
	v_div_fixup_f32 v11, v5, v11, 1.0
	v_div_scale_f32 v5, s[72:73], v10, v10, 1.0
	v_rcp_f32_e32 v6, v5
	s_nop 0
	v_fma_f32 v12, -v5, v6, 1.0
	v_fmac_f32_e32 v6, v12, v6
	v_div_scale_f32 v12, vcc, 1.0, v10, 1.0
	v_mul_f32_e32 v13, v12, v6
	v_fma_f32 v14, -v5, v13, v12
	v_fmac_f32_e32 v13, v14, v6
	v_fma_f32 v5, -v5, v13, v12
	v_div_fmas_f32 v5, v5, v6, v13
	v_div_fixup_f32 v10, v5, v10, 1.0
	v_pk_mul_f32 v[0:1], v[0:1], v[10:11]
	v_lshlrev_b32_e32 v6, 16, v7
	v_pk_mul_f32 v[0:1], v[0:1], v[8:9]
	v_pk_add_f32 v[8:9], v[64:65], 1.0 op_sel_hi:[1,0]
	v_and_b32_e32 v7, 0xffff0000, v7
	v_div_scale_f32 v5, s[72:73], v9, v9, 1.0
	v_rcp_f32_e32 v10, v5
	v_cvt_pk_bf16_f32 v0, v0, v1
	v_fma_f32 v11, -v5, v10, 1.0
	v_fmac_f32_e32 v10, v11, v10
	v_div_scale_f32 v11, vcc, 1.0, v9, 1.0
	v_mul_f32_e32 v12, v11, v10
	v_fma_f32 v13, -v5, v12, v11
	v_fmac_f32_e32 v12, v13, v10
	v_fma_f32 v5, -v5, v12, v11
	v_div_fmas_f32 v5, v5, v10, v12
	v_div_fixup_f32 v9, v5, v9, 1.0
	v_div_scale_f32 v5, s[72:73], v8, v8, 1.0
	v_rcp_f32_e32 v10, v5
	s_nop 0
	v_fma_f32 v11, -v5, v10, 1.0
	v_fmac_f32_e32 v10, v11, v10
	v_div_scale_f32 v11, vcc, 1.0, v8, 1.0
	v_mul_f32_e32 v12, v11, v10
	v_fma_f32 v13, -v5, v12, v11
	v_fmac_f32_e32 v12, v13, v10
	v_fma_f32 v5, -v5, v12, v11
	v_div_fmas_f32 v5, v5, v10, v12
	v_div_fixup_f32 v8, v5, v8, 1.0
	v_pk_mul_f32 v[2:3], v[2:3], v[8:9]
	v_mov_b32_e32 v5, v129
	v_pk_mul_f32 v[2:3], v[2:3], v[6:7]
	s_nop 0
	v_cvt_pk_bf16_f32 v1, v2, v3
	v_lshl_add_u64 v[2:3], v[4:5], 1, s[14:15]
	global_store_dwordx2 v[2:3], v[0:1], off
	s_mov_b64 s[72:73], 0
	s_and_b64 vcc, exec, s[70:71]
	s_cbranch_vccnz .LBB0_989
